# v25: v22 + attention row-sum v_pk_add_f32 split into scalar v_add_f32 pairs (packed f32 beside MFMA anti-lever, bit-identical)
# baseline (speedup 1.0000x reference)
; __device__ __forceinline__ unsigned cvt_pk_bf16(float lo, float hi) { const f32x2_t v = {lo, hi}; const bf16x2_t b = __builtin_convertvector(v, bf16x2_t); return __builtin_bit_cast(unsigned, b); }
; __device__ __forceinline__ float fast_exp2(float x) { return __builtin_amdgcn_exp2f(x); }
; template <bool WIN>
; __device__ __forceinline__ void attn_item(bf16_t* U, const float* sink, int ci, int h, LAS unsigned char* wl, const LAS float* tbl, int lane_in) {
;     ...
;     for (int s = smin; s < NS; ++s) {
;     ...
;         for (int qh = 0; qh < 2; ++qh) {
;             f32x16 C0 = Cq[qh];
;             typedef float f32x2v __attribute__((ext_vector_type(2)));
;             f32x2v ps2 = (f32x2v){0.f, 0.f};
; #pragma unroll
;             for (int r = 0; r < 16; r += 2) { C0[r] = fast_exp2(C0[r]); C0[r + 1] = fast_exp2(C0[r + 1]); ps2 += (f32x2v){C0[r], C0[r + 1]}; }
;             lrun[qh] += ps2.x + ps2.y;
;             u32x4 w0, w1;
; #pragma unroll
;             for (int q = 0; q < 4; ++q) { w0[q] = cvt_pk_bf16(C0[2 * q], C0[2 * q + 1]); w1[q] = cvt_pk_bf16(C0[8 + 2 * q], C0[8 + 2 * q + 1]); }
;             const bf16x8 pw0 = __builtin_bit_cast(bf16x8, w0), pw1 = __builtin_bit_cast(bf16x8, w1);
; #pragma unroll
;             for (int dh = 0; dh < 2; ++dh) {
;                 o[qh][dh] = __builtin_amdgcn_mfma_f32_32x32x16_bf16(vf[dh][0], pw0, o[qh][dh], 0, 0, 0);
;                 o[qh][dh] = __builtin_amdgcn_mfma_f32_32x32x16_bf16(vf[dh][1], pw1, o[qh][dh], 0, 0, 0);
;             }
;         }
.LBB0_615:
	s_nop 6
	v_exp_f32_e32 v82, v82
	v_exp_f32_e32 v83, v83
	v_exp_f32_e32 v84, v84
	v_exp_f32_e32 v85, v85
	v_exp_f32_e32 v210, v86
	v_exp_f32_e32 v211, v87
	v_add_f32_e32 v208, 0, v82
	v_add_f32_e32 v209, 0, v83
	v_exp_f32_e32 v66, v66
	v_add_f32_e32 v208, v84, v208
	v_add_f32_e32 v209, v85, v209
	v_exp_f32_e32 v67, v67
	v_add_f32_e32 v86, v210, v208
	v_add_f32_e32 v87, v211, v209
	v_exp_f32_e32 v208, v88
	v_exp_f32_e32 v209, v89
	v_cvt_pk_bf16_f32 v82, v82, v83
	v_cvt_pk_bf16_f32 v83, v84, v85
	v_cvt_pk_bf16_f32 v84, v210, v211
	v_cvt_pk_bf16_f32 v85, v208, v209
	v_exp_f32_e32 v68, v68
	v_exp_f32_e32 v69, v69
	v_mfma_f32_32x32x16_bf16 v[50:65], v[142:145], v[82:85], v[50:65]
	v_exp_f32_e32 v88, v90
	v_exp_f32_e32 v89, v91
	v_exp_f32_e32 v90, v92
	v_exp_f32_e32 v91, v93
	v_exp_f32_e32 v92, v94
	v_exp_f32_e32 v93, v95
	v_add_f32_e32 v86, v208, v86
	v_add_f32_e32 v87, v209, v87
	v_mfma_f32_32x32x16_bf16 v[34:49], v[134:137], v[82:85], v[34:49]
	v_exp_f32_e32 v84, v70
	v_exp_f32_e32 v85, v71
	v_add_f32_e32 v82, 0, v66
	v_add_f32_e32 v83, 0, v67
	v_cvt_pk_bf16_f32 v66, v66, v67
	v_add_f32_e32 v82, v68, v82
	v_add_f32_e32 v83, v69, v83
	v_cvt_pk_bf16_f32 v67, v68, v69
	v_add_f32_e32 v70, v84, v82
	v_add_f32_e32 v71, v85, v83
	v_exp_f32_e32 v82, v72
	v_exp_f32_e32 v83, v73
	v_exp_f32_e32 v72, v74
	v_exp_f32_e32 v73, v75
	v_exp_f32_e32 v74, v76
	v_exp_f32_e32 v75, v77
	v_exp_f32_e32 v76, v78
	v_exp_f32_e32 v77, v79
	v_cvt_pk_bf16_f32 v68, v84, v85
	v_cvt_pk_bf16_f32 v69, v82, v83
	v_exp_f32_e32 v94, v96
	v_exp_f32_e32 v95, v97
	v_add_f32_e32 v70, v82, v70
	v_add_f32_e32 v71, v83, v71
	v_exp_f32_e32 v78, v80
	v_exp_f32_e32 v79, v81
	v_mfma_f32_32x32x16_bf16 v[18:33], v[142:145], v[66:69], v[18:33]
	v_add_f32_e64 v86, v88, v86
	v_add_f32_e64 v87, v89, v87
	v_add_f32_e64 v70, v72, v70
	v_add_f32_e64 v71, v73, v71
	v_add_f32_e64 v86, v90, v86
	v_add_f32_e64 v87, v91, v87
	v_add_f32_e32 v70, v74, v70
	v_add_f32_e32 v71, v75, v71
	v_add_f32_e32 v86, v92, v86
	v_add_f32_e32 v87, v93, v87
	v_add_f32_e32 v70, v76, v70
	v_add_f32_e32 v71, v77, v71
	v_add_f32_e32 v96, v94, v86
	v_add_f32_e32 v97, v95, v87
	v_mfma_f32_32x32x16_bf16 v[2:17], v[134:137], v[66:69], v[2:17]
	v_add_f32_e64 v70, v78, v70
	v_add_f32_e64 v71, v79, v71
	v_mov_b32_e32 v80, v96
	v_mov_b32_e32 v81, v70
	v_mov_b32_e32 v70, v97
	v_add_f32_e32 v70, v80, v70
	v_add_f32_e32 v71, v81, v71
	v_cvt_pk_bf16_f32 v86, v88, v89
	v_cvt_pk_bf16_f32 v87, v90, v91
	v_cvt_pk_bf16_f32 v88, v92, v93
	v_cvt_pk_bf16_f32 v89, v94, v95
	v_add_f32_e32 v184, v184, v70
	v_add_f32_e32 v185, v185, v71
	v_cvt_pk_bf16_f32 v70, v72, v73
	v_cvt_pk_bf16_f32 v71, v74, v75
	v_cvt_pk_bf16_f32 v72, v76, v77
	v_cvt_pk_bf16_f32 v73, v78, v79
	v_mfma_f32_32x32x16_bf16 v[50:65], v[138:141], v[86:89], v[50:65]
	s_add_i32 s6, s21, 1
	s_add_i32 s11, s11, 32
	s_sub_i32 s36, s36, 32
	s_addk_i32 s37, 0x2000
	s_cmp_lt_u32 s21, 17
	s_mov_b32 s21, s6
	v_mfma_f32_32x32x16_bf16 v[34:49], v[130:133], v[86:89], v[34:49]
	v_mfma_f32_32x32x16_bf16 v[18:33], v[138:141], v[70:73], v[18:33]
	v_mfma_f32_32x32x16_bf16 v[2:17], v[130:133], v[70:73], v[2:17]
	s_cbranch_scc0 .LBB0_599

; __device__ __forceinline__ unsigned cvt_pk_bf16(float lo, float hi) { const f32x2_t v = {lo, hi}; const bf16x2_t b = __builtin_convertvector(v, bf16x2_t); return __builtin_bit_cast(unsigned, b); }
; __device__ __forceinline__ float fast_exp2(float x) { return __builtin_amdgcn_exp2f(x); }
; template <bool WIN>
; __device__ __forceinline__ void attn_item(bf16_t* U, const float* sink, int ci, int h, LAS unsigned char* wl, const LAS float* tbl, int lane_in) {
;     ...
;         if (s + 2 < NS) ATT_DMA(s + 2);
; #pragma unroll
;         for (int qh = 0; qh < 2; ++qh) {
;             f32x16 C0 = Cq[qh];
;             typedef float f32x2v __attribute__((ext_vector_type(2)));
;             f32x2v ps2 = (f32x2v){0.f, 0.f};
; #pragma unroll
;             for (int r = 0; r < 16; r += 2) { C0[r] = fast_exp2(C0[r]); C0[r + 1] = fast_exp2(C0[r + 1]); ps2 += (f32x2v){C0[r], C0[r + 1]}; }
;             lrun[qh] += ps2.x + ps2.y;
;             u32x4 w0, w1;
; #pragma unroll
;             for (int q = 0; q < 4; ++q) { w0[q] = cvt_pk_bf16(C0[2 * q], C0[2 * q + 1]); w1[q] = cvt_pk_bf16(C0[8 + 2 * q], C0[8 + 2 * q + 1]); }
;             const bf16x8 pw0 = __builtin_bit_cast(bf16x8, w0), pw1 = __builtin_bit_cast(bf16x8, w1);
; #pragma unroll
;             for (int dh = 0; dh < 2; ++dh) {
;                 o[qh][dh] = __builtin_amdgcn_mfma_f32_32x32x16_bf16(vf[dh][0], pw0, o[qh][dh], 0, 0, 0);
;                 o[qh][dh] = __builtin_amdgcn_mfma_f32_32x32x16_bf16(vf[dh][1], pw1, o[qh][dh], 0, 0, 0);
;             }
;         }
.L615d:
	s_mov_b32 m0, s42
	s_nop 0
	global_load_lds_dwordx4 v212, s[40:41]
	s_add_i32 m0, s42, 0x400
	s_nop 0
	global_load_lds_dwordx4 v213, s[40:41]
	s_nop 0
	v_exp_f32_e32 v82, v82
	v_exp_f32_e32 v83, v83
	v_exp_f32_e32 v84, v84
	v_exp_f32_e32 v85, v85
	v_exp_f32_e32 v210, v86
	v_exp_f32_e32 v211, v87
	v_add_f32_e32 v208, 0, v82
	v_add_f32_e32 v209, 0, v83
	v_exp_f32_e32 v66, v66
	s_add_i32 m0, s42, 0x800
	v_add_f32_e32 v208, v84, v208
	v_add_f32_e32 v209, v85, v209
	global_load_lds_dwordx4 v214, s[40:41]
	v_exp_f32_e32 v67, v67
	v_add_f32_e32 v86, v210, v208
	v_add_f32_e32 v87, v211, v209
	v_exp_f32_e32 v208, v88
	v_exp_f32_e32 v209, v89
	v_cvt_pk_bf16_f32 v82, v82, v83
	v_cvt_pk_bf16_f32 v83, v84, v85
	v_cvt_pk_bf16_f32 v84, v210, v211
	v_cvt_pk_bf16_f32 v85, v208, v209
	v_exp_f32_e32 v68, v68
	s_add_i32 m0, s42, 0xc00
	v_exp_f32_e32 v69, v69
	global_load_lds_dwordx4 v215, s[40:41]
	v_mfma_f32_32x32x16_bf16 v[50:65], v[142:145], v[82:85], v[50:65]
	v_exp_f32_e32 v88, v90
	v_exp_f32_e32 v89, v91
	v_exp_f32_e32 v90, v92
	v_exp_f32_e32 v91, v93
	v_exp_f32_e32 v92, v94
	v_exp_f32_e32 v93, v95
	v_add_f32_e32 v86, v208, v86
	v_add_f32_e32 v87, v209, v87
	v_mfma_f32_32x32x16_bf16 v[34:49], v[134:137], v[82:85], v[34:49]
	v_exp_f32_e32 v84, v70
	v_exp_f32_e32 v85, v71
	s_add_i32 m0, s42, 0x1000
	v_add_f32_e32 v82, 0, v66
	v_add_f32_e32 v83, 0, v67
	global_load_lds_dwordx4 v216, s[40:41]
	v_cvt_pk_bf16_f32 v66, v66, v67
	v_add_f32_e32 v82, v68, v82
	v_add_f32_e32 v83, v69, v83
	v_cvt_pk_bf16_f32 v67, v68, v69
	v_add_f32_e32 v70, v84, v82
	v_add_f32_e32 v71, v85, v83
	v_exp_f32_e32 v82, v72
	v_exp_f32_e32 v83, v73
	v_exp_f32_e32 v72, v74
	v_exp_f32_e32 v73, v75
	v_exp_f32_e32 v74, v76
	v_exp_f32_e32 v75, v77
	v_exp_f32_e32 v76, v78
	s_add_i32 m0, s42, 0x1400
	v_exp_f32_e32 v77, v79
	global_load_lds_dwordx4 v217, s[40:41]
	v_cvt_pk_bf16_f32 v68, v84, v85
	v_cvt_pk_bf16_f32 v69, v82, v83
	v_exp_f32_e32 v94, v96
	v_exp_f32_e32 v95, v97
	v_add_f32_e32 v70, v82, v70
	v_add_f32_e32 v71, v83, v71
	v_exp_f32_e32 v78, v80
	v_exp_f32_e32 v79, v81
	v_mfma_f32_32x32x16_bf16 v[18:33], v[142:145], v[66:69], v[18:33]
	v_add_f32_e64 v86, v88, v86
	v_add_f32_e64 v87, v89, v87
	v_add_f32_e64 v70, v72, v70
	s_add_i32 m0, s42, 0x1800
	v_add_f32_e64 v71, v73, v71
	global_load_lds_dwordx4 v218, s[40:41]
	v_add_f32_e64 v86, v90, v86
	v_add_f32_e64 v87, v91, v87
	v_add_f32_e32 v70, v74, v70
	v_add_f32_e32 v71, v75, v71
	v_add_f32_e32 v86, v92, v86
	v_add_f32_e32 v87, v93, v87
	v_add_f32_e32 v70, v76, v70
	v_add_f32_e32 v71, v77, v71
	v_add_f32_e32 v96, v94, v86
	v_add_f32_e32 v97, v95, v87
	v_mfma_f32_32x32x16_bf16 v[2:17], v[134:137], v[66:69], v[2:17]
	v_add_f32_e64 v70, v78, v70
	v_add_f32_e64 v71, v79, v71
	v_mov_b32_e32 v80, v96
	v_mov_b32_e32 v81, v70
	s_add_i32 m0, s42, 0x1c00
	v_mov_b32_e32 v70, v97
	global_load_lds_dwordx4 v219, s[40:41]
	v_add_f32_e32 v70, v80, v70
	v_add_f32_e32 v71, v81, v71
	v_cvt_pk_bf16_f32 v86, v88, v89
	v_cvt_pk_bf16_f32 v87, v90, v91
	v_cvt_pk_bf16_f32 v88, v92, v93
	v_cvt_pk_bf16_f32 v89, v94, v95
	v_add_f32_e32 v184, v184, v70
	v_add_f32_e32 v185, v185, v71
	v_cvt_pk_bf16_f32 v70, v72, v73
	v_cvt_pk_bf16_f32 v71, v74, v75
	v_cvt_pk_bf16_f32 v72, v76, v77
	v_cvt_pk_bf16_f32 v73, v78, v79
	v_mfma_f32_32x32x16_bf16 v[50:65], v[138:141], v[86:89], v[50:65]
	s_add_i32 s6, s21, 1
	s_add_i32 s11, s11, 32
	s_sub_i32 s36, s36, 32
	s_addk_i32 s37, 0x2000
	s_cmp_lt_u32 s21, 17
	s_mov_b32 s21, s6
	v_mfma_f32_32x32x16_bf16 v[34:49], v[130:133], v[86:89], v[34:49]
	v_mfma_f32_32x32x16_bf16 v[18:33], v[138:141], v[70:73], v[18:33]
	v_mfma_f32_32x32x16_bf16 v[2:17], v[130:133], v[70:73], v[2:17]
	s_cbranch_scc0 .LBB0_599
	s_branch .LBB0_616

; __device__ __forceinline__ unsigned cvt_pk_bf16(float lo, float hi) { const f32x2_t v = {lo, hi}; const bf16x2_t b = __builtin_convertvector(v, bf16x2_t); return __builtin_bit_cast(unsigned, b); }
; __device__ __forceinline__ float fast_exp2(float x) { return __builtin_amdgcn_exp2f(x); }
; template <bool WIN>
; __device__ __forceinline__ void attn_item(bf16_t* U, const float* sink, int ci, int h, LAS unsigned char* wl, const LAS float* tbl, int lane_in) {
;     ...
;         for (int qh = 0; qh < 2; ++qh) {
;             f32x16 C0 = Cq[qh];
;             typedef float f32x2v __attribute__((ext_vector_type(2)));
;             f32x2v ps2 = (f32x2v){0.f, 0.f};
; #pragma unroll
;             for (int r = 0; r < 16; r += 2) { C0[r] = fast_exp2(C0[r]); C0[r + 1] = fast_exp2(C0[r + 1]); ps2 += (f32x2v){C0[r], C0[r + 1]}; }
;             lrun[qh] += ps2.x + ps2.y;
;             u32x4 w0, w1;
; #pragma unroll
;             for (int q = 0; q < 4; ++q) { w0[q] = cvt_pk_bf16(C0[2 * q], C0[2 * q + 1]); w1[q] = cvt_pk_bf16(C0[8 + 2 * q], C0[8 + 2 * q + 1]); }
;             const bf16x8 pw0 = __builtin_bit_cast(bf16x8, w0), pw1 = __builtin_bit_cast(bf16x8, w1);
; #pragma unroll
;             for (int dh = 0; dh < 2; ++dh) {
;                 o[qh][dh] = __builtin_amdgcn_mfma_f32_32x32x16_bf16(vf[dh][0], pw0, o[qh][dh], 0, 0, 0);
;                 o[qh][dh] = __builtin_amdgcn_mfma_f32_32x32x16_bf16(vf[dh][1], pw1, o[qh][dh], 0, 0, 0);
;             }
;         }
.LBB0_646:
	s_nop 5
	v_exp_f32_e32 v66, v66
	v_exp_f32_e32 v67, v67
	v_exp_f32_e32 v68, v68
	v_exp_f32_e32 v69, v69
	v_exp_f32_e32 v242, v70
	v_exp_f32_e32 v243, v71
	v_add_f32_e32 v240, 0, v66
	v_add_f32_e32 v241, 0, v67
	v_cvt_pk_bf16_f32 v66, v66, v67
	v_add_f32_e32 v240, v68, v240
	v_add_f32_e32 v241, v69, v241
	v_cvt_pk_bf16_f32 v67, v68, v69
	v_add_f32_e32 v70, v242, v240
	v_add_f32_e32 v71, v243, v241
	v_exp_f32_e32 v240, v72
	v_exp_f32_e32 v241, v73
	v_cvt_pk_bf16_f32 v68, v242, v243
	v_exp_f32_e32 v72, v74
	v_exp_f32_e32 v73, v75
	v_cvt_pk_bf16_f32 v69, v240, v241
	v_exp_f32_e32 v74, v76
	v_exp_f32_e32 v75, v77
	v_mfma_f32_32x32x16_bf16 v[34:49], v[142:145], v[66:69], v[34:49]
	v_exp_f32_e32 v76, v78
	v_exp_f32_e32 v77, v79
	v_add_f32_e32 v70, v240, v70
	v_add_f32_e32 v71, v241, v71
	v_exp_f32_e32 v78, v80
	v_exp_f32_e32 v79, v81
	v_add_f32_e32 v70, v72, v70
	v_add_f32_e32 v71, v73, v71
	s_add_i32 s18, s55, 1
	v_mfma_f32_32x32x16_bf16 v[50:65], v[134:137], v[66:69], v[50:65]
	v_add_f32_e64 v70, v74, v70
	v_add_f32_e64 v71, v75, v71
	v_exp_f32_e32 v66, v82
	v_add_f32_e32 v70, v76, v70
	v_add_f32_e32 v71, v77, v71
	v_exp_f32_e32 v67, v83
	v_add_f32_e32 v80, v78, v70
	v_add_f32_e32 v81, v79, v71
	v_cvt_pk_bf16_f32 v70, v72, v73
	v_cvt_pk_bf16_f32 v71, v74, v75
	v_cvt_pk_bf16_f32 v72, v76, v77
	v_cvt_pk_bf16_f32 v73, v78, v79
	v_exp_f32_e32 v74, v86
	v_exp_f32_e32 v75, v87
	v_mfma_f32_32x32x16_bf16 v[34:49], v[138:141], v[70:73], v[34:49]
	v_exp_f32_e32 v76, v88
	v_exp_f32_e32 v77, v89
	v_add_f32_e32 v68, 0, v66
	v_add_f32_e32 v69, 0, v67
	v_exp_f32_e32 v78, v92
	v_exp_f32_e32 v79, v93
	v_exp_f32_e32 v82, v94
	v_exp_f32_e32 v83, v95
	v_mfma_f32_32x32x16_bf16 v[50:65], v[130:133], v[70:73], v[50:65]
	v_exp_f32_e32 v72, v84
	v_exp_f32_e32 v73, v85
	v_exp_f32_e32 v70, v90
	v_exp_f32_e32 v71, v91
	v_exp_f32_e32 v84, v96
	v_add_f32_e32 v68, v72, v68
	v_add_f32_e32 v69, v73, v69
	v_exp_f32_e32 v85, v97
	v_add_f32_e32 v68, v74, v68
	v_add_f32_e32 v69, v75, v69
	v_mov_b32_e32 v86, v80
	v_add_f32_e32 v68, v76, v68
	v_add_f32_e32 v69, v77, v69
	v_cvt_pk_bf16_f32 v66, v66, v67
	v_add_f32_e32 v68, v70, v68
	v_add_f32_e32 v69, v71, v69
	v_cvt_pk_bf16_f32 v67, v72, v73
	v_add_f32_e32 v68, v78, v68
	v_add_f32_e32 v69, v79, v69
	v_cvt_pk_bf16_f32 v70, v70, v71
	v_add_f32_e32 v68, v82, v68
	v_add_f32_e32 v69, v83, v69
	v_cvt_pk_bf16_f32 v71, v78, v79
	v_add_f32_e32 v68, v84, v68
	v_add_f32_e32 v69, v85, v69
	v_cvt_pk_bf16_f32 v72, v82, v83
	v_mov_b32_e32 v87, v68
	v_mov_b32_e32 v68, v81
	v_add_f32_e32 v68, v86, v68
	v_add_f32_e32 v69, v87, v69
	v_cvt_pk_bf16_f32 v73, v84, v85
	v_add_f32_e32 v170, v170, v68
	v_add_f32_e32 v171, v171, v69
	v_cvt_pk_bf16_f32 v68, v74, v75
	v_cvt_pk_bf16_f32 v69, v76, v77
	s_add_i32 s84, s84, 32
	s_addk_i32 s85, 0x2000
	v_mfma_f32_32x32x16_bf16 v[18:33], v[142:145], v[66:69], v[18:33]
	s_cmp_lt_u32 s55, 5
	s_mov_b32 s55, s18
	v_mfma_f32_32x32x16_bf16 v[2:17], v[134:137], v[66:69], v[2:17]
	v_mfma_f32_32x32x16_bf16 v[18:33], v[138:141], v[70:73], v[18:33]
	v_mfma_f32_32x32x16_bf16 v[2:17], v[130:133], v[70:73], v[2:17]
	s_cbranch_scc0 .LBB0_628

; __device__ __forceinline__ unsigned cvt_pk_bf16(float lo, float hi) { const f32x2_t v = {lo, hi}; const bf16x2_t b = __builtin_convertvector(v, bf16x2_t); return __builtin_bit_cast(unsigned, b); }
; __device__ __forceinline__ float fast_exp2(float x) { return __builtin_amdgcn_exp2f(x); }
; template <bool WIN>
; __device__ __forceinline__ void attn_item(bf16_t* U, const float* sink, int ci, int h, LAS unsigned char* wl, const LAS float* tbl, int lane_in) {
;     ...
;         if (s + 2 < NS) ATT_DMA(s + 2);
; #pragma unroll
;         for (int qh = 0; qh < 2; ++qh) {
;             f32x16 C0 = Cq[qh];
;             typedef float f32x2v __attribute__((ext_vector_type(2)));
;             f32x2v ps2 = (f32x2v){0.f, 0.f};
; #pragma unroll
;             for (int r = 0; r < 16; r += 2) { C0[r] = fast_exp2(C0[r]); C0[r + 1] = fast_exp2(C0[r + 1]); ps2 += (f32x2v){C0[r], C0[r + 1]}; }
;             lrun[qh] += ps2.x + ps2.y;
;             u32x4 w0, w1;
; #pragma unroll
;             for (int q = 0; q < 4; ++q) { w0[q] = cvt_pk_bf16(C0[2 * q], C0[2 * q + 1]); w1[q] = cvt_pk_bf16(C0[8 + 2 * q], C0[8 + 2 * q + 1]); }
;             const bf16x8 pw0 = __builtin_bit_cast(bf16x8, w0), pw1 = __builtin_bit_cast(bf16x8, w1);
; #pragma unroll
;             for (int dh = 0; dh < 2; ++dh) {
;                 o[qh][dh] = __builtin_amdgcn_mfma_f32_32x32x16_bf16(vf[dh][0], pw0, o[qh][dh], 0, 0, 0);
;                 o[qh][dh] = __builtin_amdgcn_mfma_f32_32x32x16_bf16(vf[dh][1], pw1, o[qh][dh], 0, 0, 0);
;             }
;         }
.L646d:
	s_mov_b32 m0, s32
	s_nop 0
	global_load_lds_dwordx4 v244, s[88:89]
	s_add_i32 m0, s32, 0x400
	s_nop 0
	global_load_lds_dwordx4 v245, s[88:89]
	v_exp_f32_e32 v66, v66
	v_exp_f32_e32 v67, v67
	v_exp_f32_e32 v68, v68
	v_exp_f32_e32 v69, v69
	v_exp_f32_e32 v242, v70
	v_exp_f32_e32 v243, v71
	v_add_f32_e32 v240, 0, v66
	v_add_f32_e32 v241, 0, v67
	v_cvt_pk_bf16_f32 v66, v66, v67
	s_add_i32 m0, s32, 0x800
	v_add_f32_e32 v240, v68, v240
	v_add_f32_e32 v241, v69, v241
	global_load_lds_dwordx4 v246, s[88:89]
	v_cvt_pk_bf16_f32 v67, v68, v69
	v_add_f32_e32 v70, v242, v240
	v_add_f32_e32 v71, v243, v241
	v_exp_f32_e32 v240, v72
	v_exp_f32_e32 v241, v73
	v_cvt_pk_bf16_f32 v68, v242, v243
	v_exp_f32_e32 v72, v74
	v_exp_f32_e32 v73, v75
	v_cvt_pk_bf16_f32 v69, v240, v241
	v_exp_f32_e32 v74, v76
	s_add_i32 m0, s32, 0xc00
	v_exp_f32_e32 v75, v77
	global_load_lds_dwordx4 v247, s[88:89]
	v_mfma_f32_32x32x16_bf16 v[34:49], v[142:145], v[66:69], v[34:49]
	v_exp_f32_e32 v76, v78
	v_exp_f32_e32 v77, v79
	v_add_f32_e32 v70, v240, v70
	v_add_f32_e32 v71, v241, v71
	v_exp_f32_e32 v78, v80
	v_exp_f32_e32 v79, v81
	v_add_f32_e32 v70, v72, v70
	v_add_f32_e32 v71, v73, v71
	s_add_i32 s18, s55, 1
	v_mfma_f32_32x32x16_bf16 v[50:65], v[134:137], v[66:69], v[50:65]
	v_add_f32_e64 v70, v74, v70
	v_add_f32_e64 v71, v75, v71
	s_add_i32 m0, s32, 0x1000
	v_exp_f32_e32 v66, v82
	global_load_lds_dwordx4 v248, s[88:89]
	v_add_f32_e32 v70, v76, v70
	v_add_f32_e32 v71, v77, v71
	v_exp_f32_e32 v67, v83
	v_add_f32_e32 v80, v78, v70
	v_add_f32_e32 v81, v79, v71
	v_cvt_pk_bf16_f32 v70, v72, v73
	v_cvt_pk_bf16_f32 v71, v74, v75
	v_cvt_pk_bf16_f32 v72, v76, v77
	v_cvt_pk_bf16_f32 v73, v78, v79
	v_exp_f32_e32 v74, v86
	v_exp_f32_e32 v75, v87
	v_mfma_f32_32x32x16_bf16 v[34:49], v[138:141], v[70:73], v[34:49]
	v_exp_f32_e32 v76, v88
	s_add_i32 m0, s32, 0x1400
	v_exp_f32_e32 v77, v89
	global_load_lds_dwordx4 v249, s[88:89]
	v_add_f32_e32 v68, 0, v66
	v_add_f32_e32 v69, 0, v67
	v_exp_f32_e32 v78, v92
	v_exp_f32_e32 v79, v93
	v_exp_f32_e32 v82, v94
	v_exp_f32_e32 v83, v95
	v_mfma_f32_32x32x16_bf16 v[50:65], v[130:133], v[70:73], v[50:65]
	v_exp_f32_e32 v72, v84
	v_exp_f32_e32 v73, v85
	v_exp_f32_e32 v70, v90
	v_exp_f32_e32 v71, v91
	v_exp_f32_e32 v84, v96
	s_add_i32 m0, s32, 0x1800
	v_add_f32_e32 v68, v72, v68
	v_add_f32_e32 v69, v73, v69
	global_load_lds_dwordx4 v250, s[88:89]
	v_exp_f32_e32 v85, v97
	v_add_f32_e32 v68, v74, v68
	v_add_f32_e32 v69, v75, v69
	v_mov_b32_e32 v86, v80
	v_add_f32_e32 v68, v76, v68
	v_add_f32_e32 v69, v77, v69
	v_cvt_pk_bf16_f32 v66, v66, v67
	v_add_f32_e32 v68, v70, v68
	v_add_f32_e32 v69, v71, v69
	v_cvt_pk_bf16_f32 v67, v72, v73
	v_add_f32_e32 v68, v78, v68
	v_add_f32_e32 v69, v79, v69
	v_cvt_pk_bf16_f32 v70, v70, v71
	v_add_f32_e32 v68, v82, v68
	v_add_f32_e32 v69, v83, v69
	v_cvt_pk_bf16_f32 v71, v78, v79
	s_add_i32 m0, s32, 0x1c00
	v_add_f32_e32 v68, v84, v68
	v_add_f32_e32 v69, v85, v69
	global_load_lds_dwordx4 v251, s[88:89]
	v_cvt_pk_bf16_f32 v72, v82, v83
	v_mov_b32_e32 v87, v68
	v_mov_b32_e32 v68, v81
	v_add_f32_e32 v68, v86, v68
	v_add_f32_e32 v69, v87, v69
	v_cvt_pk_bf16_f32 v73, v84, v85
	v_add_f32_e32 v170, v170, v68
	v_add_f32_e32 v171, v171, v69
	v_cvt_pk_bf16_f32 v68, v74, v75
	v_cvt_pk_bf16_f32 v69, v76, v77
	s_add_i32 s84, s84, 32
	s_addk_i32 s85, 0x2000
	v_mfma_f32_32x32x16_bf16 v[18:33], v[142:145], v[66:69], v[18:33]
	s_cmp_lt_u32 s55, 5
	s_mov_b32 s55, s18
	v_mfma_f32_32x32x16_bf16 v[2:17], v[134:137], v[66:69], v[2:17]
	v_mfma_f32_32x32x16_bf16 v[18:33], v[138:141], v[70:73], v[18:33]
	v_mfma_f32_32x32x16_bf16 v[2:17], v[130:133], v[70:73], v[2:17]
	s_cbranch_scc0 .LBB0_628
	s_branch .LBB0_647
